# final_norm_pipelined_plus_fixup2
# speedup vs baseline: 1.0070x; 1.0070x over previous
.LBB0_1040:
	v_readlane_b32 s3, v253, 2
	v_readfirstlane_b32 s0, v165
	s_ashr_i32 s0, s0, 6
	s_add_i32 s8, s0, s3
	s_cmpk_gt_i32 s8, 0x7fff
	v_readlane_b32 s14, v253, 4
	v_readlane_b32 s15, v253, 5
	s_cbranch_scc1 .LBB0_1043
	s_load_dwordx4 s[4:7], s[84:85], 0x80
	s_load_dwordx2 s[10:11], s[84:85], 0x90
	s_ashr_i32 s1, s0, 31
	s_ashr_i32 s2, s3, 31
	s_add_u32 s12, s0, s3
	s_addc_u32 s13, s1, s2
	s_lshl_b64 s[0:1], s[12:13], 2
	s_waitcnt lgkmcnt(0)
	s_add_u32 s0, s10, s0
	s_addc_u32 s1, s11, s1
	v_and_b32_e32 v6, 63, v165
	s_add_u32 s0, s0, 0x3280000
	v_mov_b32_e32 v1, 0
	v_lshlrev_b32_e32 v0, 4, v6
	s_addc_u32 s1, s1, 0
	s_ashr_i32 s15, s14, 31
	v_lshl_add_u64 v[2:3], s[4:5], 0, v[0:1]
	s_lshl_b64 s[2:3], s[14:15], 2
	s_lshl_b64 s[4:5], s[12:13], 12
	s_add_u32 s4, s6, s4
	s_addc_u32 s5, s7, s5
	v_lshl_add_u64 v[4:5], s[4:5], 0, v[0:1]
	s_mov_b64 s[4:5], 0xc00
	v_lshl_add_u64 v[4:5], v[4:5], 0, s[4:5]
	s_lshl_b64 s[4:5], s[14:15], 12
	s_lshl_b64 s[6:7], s[12:13], 11
	s_add_u32 s6, s10, s6
	v_lshlrev_b32_e32 v0, 3, v6
	s_addc_u32 s7, s11, s7
	v_lshl_add_u64 v[6:7], s[6:7], 0, v[0:1]
	s_mov_b64 s[6:7], 0x4500400
	v_lshl_add_u64 v[6:7], v[6:7], 0, s[6:7]
	s_lshl_b64 s[6:7], s[14:15], 11
	v_mov_b32_e32 v0, 0x358637bd
	s_mov_b32 s9, 0x800000
	global_load_dwordx4 v[20:23], v[2:3], off
	global_load_dwordx4 v[24:27], v[2:3], off offset:1024
	global_load_dwordx4 v[28:31], v[2:3], off offset:2048
	global_load_dwordx4 v[32:35], v[2:3], off offset:3072
	global_load_dword v14, v1, s[0:1]
	global_load_dwordx2 v[36:37], v[6:7], off offset:-1024
	global_load_dwordx2 v[38:39], v[6:7], off offset:-512
	global_load_dwordx2 v[40:41], v[6:7], off
	global_load_dwordx2 v[42:43], v[6:7], off offset:512
	s_waitcnt vmcnt(0)
.LBB0_1042:
	s_add_i32 s10, s8, s14
	s_cmpk_gt_i32 s10, 0x7fff
	s_cselect_b64 s[16:17], 0, s[2:3]
	s_cselect_b64 s[18:19], 0, s[6:7]
	s_add_u32 s0, s0, s16
	s_addc_u32 s1, s1, s17
	v_lshl_add_u64 v[6:7], s[18:19], 0, v[6:7]
	global_load_dword v15, v1, s[0:1]
	global_load_dwordx2 v[44:45], v[6:7], off offset:-1024
	global_load_dwordx2 v[46:47], v[6:7], off offset:-512
	global_load_dwordx2 v[48:49], v[6:7], off
	global_load_dwordx2 v[50:51], v[6:7], off offset:512
	s_waitcnt vmcnt(9)
	v_fmamk_f32 v16, v14, 0x3a800000, v0
	v_mul_f32_e32 v17, 0x4b800000, v16
	v_cmp_gt_f32_e32 vcc, s9, v16
	v_lshlrev_b32_e32 v52, 16, v36
	v_and_b32_e32 v53, 0xffff0000, v36
	v_lshlrev_b32_e32 v54, 16, v37
	v_and_b32_e32 v55, 0xffff0000, v37
	v_cndmask_b32_e32 v16, v16, v17, vcc
	v_rsq_f32_e32 v16, v16
	v_lshlrev_b32_e32 v56, 16, v38
	v_and_b32_e32 v57, 0xffff0000, v38
	v_lshlrev_b32_e32 v58, 16, v39
	v_and_b32_e32 v59, 0xffff0000, v39
	v_mul_f32_e32 v17, 0x45800000, v16
	v_lshlrev_b32_e32 v60, 16, v40
	v_and_b32_e32 v61, 0xffff0000, v40
	v_lshlrev_b32_e32 v62, 16, v41
	v_and_b32_e32 v63, 0xffff0000, v41
	v_cndmask_b32_e32 v16, v16, v17, vcc
	v_lshlrev_b32_e32 v64, 16, v42
	v_and_b32_e32 v65, 0xffff0000, v42
	v_lshlrev_b32_e32 v66, 16, v43
	v_and_b32_e32 v67, 0xffff0000, v43
	v_pk_mul_f32 v[52:53], v[16:17], v[52:53] op_sel_hi:[0,1]
	v_pk_mul_f32 v[54:55], v[16:17], v[54:55] op_sel_hi:[0,1]
	v_pk_mul_f32 v[52:53], v[20:21], v[52:53]
	v_pk_mul_f32 v[54:55], v[22:23], v[54:55]
	global_store_dwordx4 v[4:5], v[52:55], off offset:-3072
	v_pk_mul_f32 v[56:57], v[16:17], v[56:57] op_sel_hi:[0,1]
	v_pk_mul_f32 v[58:59], v[16:17], v[58:59] op_sel_hi:[0,1]
	v_pk_mul_f32 v[56:57], v[24:25], v[56:57]
	v_pk_mul_f32 v[58:59], v[26:27], v[58:59]
	global_store_dwordx4 v[4:5], v[56:59], off offset:-2048
	v_pk_mul_f32 v[60:61], v[16:17], v[60:61] op_sel_hi:[0,1]
	v_pk_mul_f32 v[62:63], v[16:17], v[62:63] op_sel_hi:[0,1]
	v_pk_mul_f32 v[60:61], v[28:29], v[60:61]
	v_pk_mul_f32 v[62:63], v[30:31], v[62:63]
	global_store_dwordx4 v[4:5], v[60:63], off offset:-1024
	v_pk_mul_f32 v[64:65], v[16:17], v[64:65] op_sel_hi:[0,1]
	v_pk_mul_f32 v[66:67], v[16:17], v[66:67] op_sel_hi:[0,1]
	v_pk_mul_f32 v[64:65], v[32:33], v[64:65]
	v_pk_mul_f32 v[66:67], v[34:35], v[66:67]
	global_store_dwordx4 v[4:5], v[64:67], off
	v_lshl_add_u64 v[4:5], v[4:5], 0, s[4:5]
	s_mov_b32 s8, s10
	s_cmpk_gt_i32 s8, 0x7fff
	s_cbranch_scc1 .LBB0_1043
	s_add_i32 s10, s8, s14
	s_cmpk_gt_i32 s10, 0x7fff
	s_cselect_b64 s[16:17], 0, s[2:3]
	s_cselect_b64 s[18:19], 0, s[6:7]
	s_add_u32 s0, s0, s16
	s_addc_u32 s1, s1, s17
	v_lshl_add_u64 v[6:7], s[18:19], 0, v[6:7]
	global_load_dword v14, v1, s[0:1]
	global_load_dwordx2 v[36:37], v[6:7], off offset:-1024
	global_load_dwordx2 v[38:39], v[6:7], off offset:-512
	global_load_dwordx2 v[40:41], v[6:7], off
	global_load_dwordx2 v[42:43], v[6:7], off offset:512
	s_waitcnt vmcnt(9)
	v_fmamk_f32 v16, v15, 0x3a800000, v0
	v_mul_f32_e32 v17, 0x4b800000, v16
	v_cmp_gt_f32_e32 vcc, s9, v16
	v_lshlrev_b32_e32 v52, 16, v44
	v_and_b32_e32 v53, 0xffff0000, v44
	v_lshlrev_b32_e32 v54, 16, v45
	v_and_b32_e32 v55, 0xffff0000, v45
	v_cndmask_b32_e32 v16, v16, v17, vcc
	v_rsq_f32_e32 v16, v16
	v_lshlrev_b32_e32 v56, 16, v46
	v_and_b32_e32 v57, 0xffff0000, v46
	v_lshlrev_b32_e32 v58, 16, v47
	v_and_b32_e32 v59, 0xffff0000, v47
	v_mul_f32_e32 v17, 0x45800000, v16
	v_lshlrev_b32_e32 v60, 16, v48
	v_and_b32_e32 v61, 0xffff0000, v48
	v_lshlrev_b32_e32 v62, 16, v49
	v_and_b32_e32 v63, 0xffff0000, v49
	v_cndmask_b32_e32 v16, v16, v17, vcc
	v_lshlrev_b32_e32 v64, 16, v50
	v_and_b32_e32 v65, 0xffff0000, v50
	v_lshlrev_b32_e32 v66, 16, v51
	v_and_b32_e32 v67, 0xffff0000, v51
	v_pk_mul_f32 v[52:53], v[16:17], v[52:53] op_sel_hi:[0,1]
	v_pk_mul_f32 v[54:55], v[16:17], v[54:55] op_sel_hi:[0,1]
	v_pk_mul_f32 v[52:53], v[20:21], v[52:53]
	v_pk_mul_f32 v[54:55], v[22:23], v[54:55]
	global_store_dwordx4 v[4:5], v[52:55], off offset:-3072
	v_pk_mul_f32 v[56:57], v[16:17], v[56:57] op_sel_hi:[0,1]
	v_pk_mul_f32 v[58:59], v[16:17], v[58:59] op_sel_hi:[0,1]
	v_pk_mul_f32 v[56:57], v[24:25], v[56:57]
	v_pk_mul_f32 v[58:59], v[26:27], v[58:59]
	global_store_dwordx4 v[4:5], v[56:59], off offset:-2048
	v_pk_mul_f32 v[60:61], v[16:17], v[60:61] op_sel_hi:[0,1]
	v_pk_mul_f32 v[62:63], v[16:17], v[62:63] op_sel_hi:[0,1]
	v_pk_mul_f32 v[60:61], v[28:29], v[60:61]
	v_pk_mul_f32 v[62:63], v[30:31], v[62:63]
	global_store_dwordx4 v[4:5], v[60:63], off offset:-1024
	v_pk_mul_f32 v[64:65], v[16:17], v[64:65] op_sel_hi:[0,1]
	v_pk_mul_f32 v[66:67], v[16:17], v[66:67] op_sel_hi:[0,1]
	v_pk_mul_f32 v[64:65], v[32:33], v[64:65]
	v_pk_mul_f32 v[66:67], v[34:35], v[66:67]
	global_store_dwordx4 v[4:5], v[64:67], off
	v_lshl_add_u64 v[4:5], v[4:5], 0, s[4:5]
	s_mov_b32 s8, s10
	s_cmpk_gt_i32 s8, 0x7fff
	s_cbranch_scc1 .LBB0_1043
	s_branch .LBB0_1042
